# H-store cache policy mix: first 3 rows write-through, last 5 default policy
# speedup vs baseline: 1.0053x; 1.0053x over previous
; __device__ __forceinline__ void load_rs8(const float* ssq, unsigned row0, int fq, float (&rs)[8]) {
;     f32x4 p[8];
; #pragma unroll
;     for (int k = 0; k < 8; ++k) p[k] = *(const f32x4*)(ssq + ((row0 + (k >> 2) * 128 + (k & 3) * 16) * 16u + fq * 4));
; #pragma unroll
;     for (int k = 0; k < 8; ++k) { float s = (p[k][0] + p[k][1]) + (p[k][2] + p[k][3]); s += __shfl_xor(s, 16); s += __shfl_xor(s, 32); rs[k] = rsqrtf(s * (1.0f / 1024.0f) + RMS_EPS); }
; }
;     __device__ __forceinline__ void operator()(const f32x4 (&acc)[2][2][4][2], const pg8::Unit& u, int wr, int wc, int fr, int fq) const {
;         const unsigned row0 = u.pm * 256 + wr * 64 + fr;
;         if (kind == 0) {
;             bf16_t* H = (bf16_t*)(R + R_H); const unsigned col0 = u.pn * 128 + wc * 32 + 8 * fq;
;             float rs8[8]; load_rs8(ssq, row0, fq, rs8);
.LBB0_179:
	s_cmp_eq_u32 s9, 1
	s_mov_b64 s[0:1], -1
	s_cbranch_scc1 .LBB0_181
	v_lshlrev_b32_e32 v132, 4, v232
	v_readlane_b32 s0, v250, 29
	v_or_b32_e32 v0, v132, v224
	v_readlane_b32 s1, v250, 30
	s_mov_b32 s24, 0x3a800000
	s_mov_b32 s2, 0x800000
	v_lshl_add_u64 v[130:131], v[0:1], 2, s[0:1]
	global_load_dwordx4 v[160:163], v[130:131], off
	v_or_b32_e32 v130, 0x100, v0
	v_mov_b32_e32 v131, v1
	v_lshl_add_u64 v[130:131], v[130:131], 2, s[0:1]
	global_load_dwordx4 v[164:167], v[130:131], off
	v_or_b32_e32 v130, 0x200, v0
	v_mov_b32_e32 v131, v1
	v_lshl_add_u64 v[130:131], v[130:131], 2, s[0:1]
	v_or_b32_e32 v0, 0x300, v0
	global_load_dwordx4 v[150:153], v[130:131], off
	v_lshl_add_u64 v[130:131], v[0:1], 2, s[0:1]
	global_load_dwordx4 v[146:149], v[130:131], off
	v_add_u32_e32 v0, v132, v225
	v_lshl_add_u64 v[130:131], v[0:1], 2, s[0:1]
	v_add_u32_e32 v0, v132, v226
	global_load_dwordx4 v[142:145], v[130:131], off
	v_lshl_add_u64 v[130:131], v[0:1], 2, s[0:1]
	global_load_dwordx4 v[138:141], v[130:131], off
	v_add_u32_e32 v0, v132, v227
	v_lshl_add_u64 v[130:131], v[0:1], 2, s[0:1]
	v_add_u32_e32 v0, v132, v228
	global_load_dwordx4 v[134:137], v[130:131], off
	v_lshl_add_u64 v[130:131], v[0:1], 2, s[0:1]
	global_load_dwordx4 v[130:133], v[130:131], off
	v_mbcnt_hi_u32_b32 v0, -1, v212
	v_and_b32_e32 v155, 64, v0
	v_xor_b32_e32 v154, 16, v0
	v_add_u32_e32 v155, 64, v155
	v_cmp_lt_i32_e32 vcc, v154, v155
	s_mov_b32 s0, 0x358637bd
	s_waitcnt vmcnt(0)
	v_mov_b32_e32 v156, v161
	v_mov_b32_e32 v157, v162
	v_mov_b32_e32 v161, v163
	v_pk_add_f32 v[156:157], v[156:157], v[160:161]
	v_mov_b32_e32 v160, v165
	v_mov_b32_e32 v161, v166
	v_mov_b32_e32 v165, v167
	v_pk_add_f32 v[160:161], v[160:161], v[164:165]
	v_cndmask_b32_e32 v154, v0, v154, vcc
	v_mov_b32_e32 v162, v160
	v_mov_b32_e32 v163, v156
	v_mov_b32_e32 v156, v161
	v_lshlrev_b32_e32 v158, 2, v154
	v_pk_add_f32 v[156:157], v[162:163], v[156:157]
	ds_bpermute_b32 v161, v158, v157
	ds_bpermute_b32 v160, v158, v156
	v_xor_b32_e32 v154, 32, v0
	v_cmp_lt_i32_e32 vcc, v154, v155
	s_waitcnt lgkmcnt(0)
	v_pk_add_f32 v[156:157], v[156:157], v[160:161]
	v_cndmask_b32_e32 v0, v0, v154, vcc
	v_lshlrev_b32_e32 v155, 2, v0
	ds_bpermute_b32 v161, v155, v157
	ds_bpermute_b32 v160, v155, v156
	s_waitcnt lgkmcnt(0)
	v_pk_add_f32 v[160:161], v[156:157], v[160:161]
	v_mov_b64_e32 v[156:157], s[0:1]
	v_pk_fma_f32 v[160:161], v[160:161], s[24:25], v[156:157] op_sel_hi:[1,0,0]
	s_nop 0
	v_mul_f32_e32 v0, 0x4b800000, v161
	v_cmp_gt_f32_e64 s[0:1], s2, v161
	v_cmp_gt_f32_e32 vcc, s2, v160
	s_nop 0
	v_cndmask_b32_e64 v0, v161, v0, s[0:1]
	v_rsq_f32_e32 v0, v0
	v_mov_b32_e32 v161, v152
	v_mov_b32_e32 v152, v147
	v_mov_b32_e32 v147, v149
	v_mul_f32_e32 v154, 0x45800000, v0
	v_cndmask_b32_e64 v154, v0, v154, s[0:1]
	v_mul_f32_e32 v0, 0x4b800000, v160
	v_cndmask_b32_e32 v0, v160, v0, vcc
	v_mov_b32_e32 v160, v151
	v_mov_b32_e32 v151, v153
	v_mov_b32_e32 v153, v148
	v_pk_add_f32 v[150:151], v[160:161], v[150:151]
	v_pk_add_f32 v[146:147], v[152:153], v[146:147]
	v_mov_b32_e32 v149, v150
	v_mov_b32_e32 v148, v146
	v_mov_b32_e32 v150, v147
	v_pk_add_f32 v[146:147], v[148:149], v[150:151]
	ds_bpermute_b32 v149, v158, v147
	ds_bpermute_b32 v148, v158, v146
	v_mov_b32_e32 v150, v143
	v_mov_b32_e32 v151, v144
	v_mov_b32_e32 v143, v145
	v_mov_b32_e32 v144, v139
	v_mov_b32_e32 v145, v140
	v_mov_b32_e32 v139, v141
	v_pk_add_f32 v[142:143], v[150:151], v[142:143]
	v_pk_add_f32 v[138:139], v[144:145], v[138:139]
	s_waitcnt lgkmcnt(0)
	v_pk_add_f32 v[146:147], v[146:147], v[148:149]
	v_mov_b32_e32 v140, v138
	v_mov_b32_e32 v141, v142
	v_mov_b32_e32 v142, v139
	ds_bpermute_b32 v149, v155, v147
	ds_bpermute_b32 v148, v155, v146
	v_pk_add_f32 v[138:139], v[140:141], v[142:143]
	ds_bpermute_b32 v141, v158, v139
	ds_bpermute_b32 v140, v158, v138
	v_mov_b32_e32 v142, v135
	v_mov_b32_e32 v143, v136
	v_mov_b32_e32 v135, v137
	v_mov_b32_e32 v136, v131
	v_mov_b32_e32 v137, v132
	v_mov_b32_e32 v131, v133
	s_waitcnt lgkmcnt(2)
	v_pk_add_f32 v[146:147], v[146:147], v[148:149]
	v_pk_add_f32 v[134:135], v[142:143], v[134:135]
	v_pk_add_f32 v[130:131], v[136:137], v[130:131]
	v_pk_fma_f32 v[146:147], v[146:147], s[24:25], v[156:157] op_sel_hi:[1,0,0]
	s_waitcnt lgkmcnt(0)
	v_pk_add_f32 v[138:139], v[138:139], v[140:141]
	v_mov_b32_e32 v132, v130
	v_mov_b32_e32 v133, v134
	v_mov_b32_e32 v134, v131
	v_mul_f32_e32 v148, 0x4b800000, v147
	v_cmp_gt_f32_e64 s[0:1], s2, v147
	ds_bpermute_b32 v141, v155, v139
	ds_bpermute_b32 v140, v155, v138
	v_pk_add_f32 v[130:131], v[132:133], v[134:135]
	v_cndmask_b32_e64 v147, v147, v148, s[0:1]
	ds_bpermute_b32 v133, v158, v131
	ds_bpermute_b32 v132, v158, v130
	v_rsq_f32_e32 v0, v0
	v_rsq_f32_e32 v147, v147
	s_waitcnt lgkmcnt(2)
	v_pk_add_f32 v[138:139], v[138:139], v[140:141]
	v_pk_mul_f32 v[136:137], v[126:127], v[154:155] op_sel_hi:[1,0]
	v_mul_f32_e32 v159, 0x45800000, v0
	v_mul_f32_e32 v148, 0x45800000, v147
	v_pk_fma_f32 v[138:139], v[138:139], s[24:25], v[156:157] op_sel_hi:[1,0,0]
	s_waitcnt lgkmcnt(0)
	v_pk_add_f32 v[130:131], v[130:131], v[132:133]
	v_cndmask_b32_e32 v0, v0, v159, vcc
	v_cmp_gt_f32_e32 vcc, s2, v146
	v_cndmask_b32_e64 v148, v147, v148, s[0:1]
	v_mul_f32_e32 v147, 0x4b800000, v146
	v_mul_f32_e32 v140, 0x4b800000, v139
	v_cmp_gt_f32_e64 s[0:1], s2, v139
	ds_bpermute_b32 v133, v155, v131
	ds_bpermute_b32 v132, v155, v130
	v_cndmask_b32_e32 v146, v146, v147, vcc
	v_cndmask_b32_e64 v139, v139, v140, s[0:1]
	v_rsq_f32_e32 v146, v146
	v_rsq_f32_e32 v139, v139
	s_waitcnt lgkmcnt(0)
; __device__ __forceinline__ unsigned pk2(float lo, float hi) { f32x2_t v = {lo, hi}; bf16x2_t b = __builtin_convertvector(v, bf16x2_t); return __builtin_bit_cast(unsigned, b); }
; __device__ __forceinline__ float fast_sigmoid(float z) { return __builtin_amdgcn_rcpf(1.0f + __expf(-z)); }
;     __device__ __forceinline__ void operator()(const f32x4 (&acc)[2][2][4][2], const pg8::Unit& u, int wr, int wc, int fr, int fq) const {
;     ...
; #pragma unroll
;             for (int ai = 0; ai < 2; ++ai)
; #pragma unroll
;                 for (int m = 0; m < 4; ++m) {
;                     const unsigned row = row0 + ai * 128 + m * 16; const float rs = rs8[ai * 4 + m];
;                     u32x4 w;
; #pragma unroll
;                     for (int n = 0; n < 2; ++n) {
;                         const f32x4 g = acc[ai][0][m][n] * rs, up = acc[ai][1][m][n] * rs; f32x4 hh;
; #pragma unroll
;                         for (int i = 0; i < 4; ++i) hh[i] = g[i] * fast_sigmoid(g[i]) * up[i];
;                         w[2 * n] = pk2(hh[0], hh[1]); w[2 * n + 1] = pk2(hh[2], hh[3]);
;                     }
;                     { bf16_t* hp_ = H + (row * (unsigned)FF + col0); asm volatile("global_store_dwordx4 %0, %1, off " H_STORE_BITS "\n\ts_nop 1" :: "v"(hp_), "v"(w) : "memory"); }
	v_pk_add_f32 v[130:131], v[130:131], v[132:133]
	v_lshl_or_b32 v134, s55, 7, v229
	v_mul_f32_e32 v147, 0x45800000, v146
	v_mul_f32_e32 v140, 0x45800000, v139
	v_pk_fma_f32 v[130:131], v[130:131], s[24:25], v[156:157] op_sel_hi:[1,0,0]
	v_cndmask_b32_e32 v146, v146, v147, vcc
	v_cmp_gt_f32_e32 vcc, s2, v138
	v_cndmask_b32_e64 v140, v139, v140, s[0:1]
	v_mul_f32_e32 v139, 0x4b800000, v138
	v_mul_f32_e32 v132, 0x4b800000, v131
	v_cmp_gt_f32_e64 s[0:1], s2, v131
	v_cndmask_b32_e32 v138, v138, v139, vcc
	v_rsq_f32_e32 v138, v138
	v_cndmask_b32_e64 v131, v131, v132, s[0:1]
	v_rsq_f32_e32 v131, v131
	v_mul_f32_e32 v139, 0x45800000, v138
	v_cndmask_b32_e32 v138, v138, v139, vcc
	v_mul_f32_e32 v132, 0x45800000, v131
	v_cmp_gt_f32_e32 vcc, s2, v130
	v_cndmask_b32_e64 v132, v131, v132, s[0:1]
	v_mul_f32_e32 v131, 0x4b800000, v130
	v_cndmask_b32_e32 v130, v130, v131, vcc
	v_rsq_f32_e32 v130, v130
	s_movk_i32 s0, 0xb00
	v_mad_u64_u32 v[134:135], s[0:1], v232, s0, v[134:135]
	v_mul_f32_e32 v131, 0x45800000, v130
	v_cndmask_b32_e32 v130, v130, v131, vcc
	v_mul_f32_e32 v131, 0xbfb8aa3b, v136
	v_exp_f32_e32 v131, v131
	v_readlane_b32 s0, v250, 39
	v_mov_b32_e32 v135, v1
	v_readlane_b32 s1, v250, 40
	v_add_f32_e32 v131, 1.0, v131
	v_rcp_f32_e32 v142, v131
	v_mul_f32_e32 v131, 0xbfb8aa3b, v137
	v_exp_f32_e32 v131, v131
	s_nop 0
	v_add_f32_e32 v131, 1.0, v131
	v_rcp_f32_e32 v143, v131
	s_nop 0
	v_pk_mul_f32 v[136:137], v[136:137], v[142:143]
	v_pk_mul_f32 v[142:143], v[118:119], v[154:155] op_sel_hi:[1,0]
	s_nop 0
	v_pk_mul_f32 v[136:137], v[142:143], v[136:137]
	v_pk_mul_f32 v[142:143], v[128:129], v[154:155] op_sel_hi:[1,0]
	s_nop 0
	v_mul_f32_e32 v131, 0xbfb8aa3b, v142
	v_exp_f32_e32 v131, v131
	s_nop 0
	v_add_f32_e32 v131, 1.0, v131
	v_rcp_f32_e32 v144, v131
	v_mul_f32_e32 v131, 0xbfb8aa3b, v143
	v_exp_f32_e32 v131, v131
	s_nop 0
	v_add_f32_e32 v131, 1.0, v131
	v_rcp_f32_e32 v145, v131
	s_nop 0
	v_pk_mul_f32 v[142:143], v[142:143], v[144:145]
	v_pk_mul_f32 v[144:145], v[120:121], v[154:155] op_sel_hi:[1,0]
	s_nop 0
	v_pk_mul_f32 v[144:145], v[144:145], v[142:143]
	v_cvt_pk_bf16_f32 v142, v136, v137
	v_pk_mul_f32 v[136:137], v[122:123], v[154:155] op_sel_hi:[1,0]
	v_cvt_pk_bf16_f32 v143, v144, v145
	v_mul_f32_e32 v131, 0xbfb8aa3b, v136
	v_exp_f32_e32 v131, v131
	s_nop 0
	v_add_f32_e32 v131, 1.0, v131
	v_rcp_f32_e32 v144, v131
	v_mul_f32_e32 v131, 0xbfb8aa3b, v137
	v_exp_f32_e32 v131, v131
	s_nop 0
	v_add_f32_e32 v131, 1.0, v131
	v_rcp_f32_e32 v145, v131
	s_nop 0
	v_pk_mul_f32 v[136:137], v[136:137], v[144:145]
	v_pk_mul_f32 v[144:145], v[114:115], v[154:155] op_sel_hi:[1,0]
	s_nop 0
	v_pk_mul_f32 v[136:137], v[144:145], v[136:137]
	v_pk_mul_f32 v[144:145], v[124:125], v[154:155] op_sel_hi:[1,0]
	s_nop 0
	v_mul_f32_e32 v131, 0xbfb8aa3b, v144
	v_exp_f32_e32 v131, v131
	s_nop 0
	v_add_f32_e32 v131, 1.0, v131
	v_rcp_f32_e32 v150, v131
	v_mul_f32_e32 v131, 0xbfb8aa3b, v145
	v_exp_f32_e32 v131, v131
	s_nop 0
	v_add_f32_e32 v131, 1.0, v131
	v_rcp_f32_e32 v151, v131
	s_nop 0
	v_pk_mul_f32 v[144:145], v[144:145], v[150:151]
	v_pk_mul_f32 v[150:151], v[116:117], v[154:155] op_sel_hi:[1,0]
	s_nop 0
	v_pk_mul_f32 v[150:151], v[150:151], v[144:145]
	v_cvt_pk_bf16_f32 v144, v136, v137
	v_lshl_add_u64 v[136:137], v[134:135], 1, s[0:1]
	v_cvt_pk_bf16_f32 v145, v150, v151
	global_store_dwordx4 v[136:137], v[142:145], off sc0 sc1
	s_nop 1
	v_pk_mul_f32 v[136:137], v[110:111], v[0:1] op_sel_hi:[1,0]
	s_nop 0
	v_mul_f32_e32 v131, 0xbfb8aa3b, v136
	v_exp_f32_e32 v131, v131
	s_nop 0
	v_add_f32_e32 v131, 1.0, v131
	v_rcp_f32_e32 v142, v131
	v_mul_f32_e32 v131, 0xbfb8aa3b, v137
	v_exp_f32_e32 v131, v131
	s_nop 0
	v_add_f32_e32 v131, 1.0, v131
	v_rcp_f32_e32 v143, v131
	s_nop 0
	v_pk_mul_f32 v[136:137], v[136:137], v[142:143]
	v_pk_mul_f32 v[142:143], v[102:103], v[0:1] op_sel_hi:[1,0]
	s_nop 0
	v_pk_mul_f32 v[136:137], v[142:143], v[136:137]
	v_pk_mul_f32 v[142:143], v[112:113], v[0:1] op_sel_hi:[1,0]
	s_nop 0
	v_mul_f32_e32 v131, 0xbfb8aa3b, v142
	v_exp_f32_e32 v131, v131
	s_nop 0
	v_add_f32_e32 v131, 1.0, v131
	v_rcp_f32_e32 v144, v131
	v_mul_f32_e32 v131, 0xbfb8aa3b, v143
	v_exp_f32_e32 v131, v131
	s_nop 0
	v_add_f32_e32 v131, 1.0, v131
	v_rcp_f32_e32 v145, v131
	s_nop 0
	v_pk_mul_f32 v[142:143], v[142:143], v[144:145]
	v_pk_mul_f32 v[144:145], v[104:105], v[0:1] op_sel_hi:[1,0]
	s_nop 0
	v_pk_mul_f32 v[144:145], v[144:145], v[142:143]
	v_cvt_pk_bf16_f32 v142, v136, v137
	v_pk_mul_f32 v[136:137], v[106:107], v[0:1] op_sel_hi:[1,0]
	v_cvt_pk_bf16_f32 v143, v144, v145
	v_mul_f32_e32 v131, 0xbfb8aa3b, v136
	v_exp_f32_e32 v131, v131
	s_nop 0
	v_add_f32_e32 v131, 1.0, v131
	v_rcp_f32_e32 v144, v131
	v_mul_f32_e32 v131, 0xbfb8aa3b, v137
	v_exp_f32_e32 v131, v131
	s_nop 0
	v_add_f32_e32 v131, 1.0, v131
	v_rcp_f32_e32 v145, v131
	s_nop 0
	v_pk_mul_f32 v[136:137], v[136:137], v[144:145]
	v_pk_mul_f32 v[144:145], v[98:99], v[0:1] op_sel_hi:[1,0]
	s_nop 0
	v_pk_mul_f32 v[136:137], v[144:145], v[136:137]
	v_pk_mul_f32 v[144:145], v[108:109], v[0:1] op_sel_hi:[1,0]
	s_nop 0
	v_mul_f32_e32 v131, 0xbfb8aa3b, v144
	v_exp_f32_e32 v131, v131
	s_nop 0
	v_add_f32_e32 v131, 1.0, v131
	v_rcp_f32_e32 v150, v131
	v_mul_f32_e32 v131, 0xbfb8aa3b, v145
	v_exp_f32_e32 v131, v131
	s_nop 0
	v_add_f32_e32 v131, 1.0, v131
	v_rcp_f32_e32 v151, v131
	s_nop 0
	v_pk_mul_f32 v[144:145], v[144:145], v[150:151]
	v_pk_mul_f32 v[150:151], v[100:101], v[0:1] op_sel_hi:[1,0]
	v_add_u32_e32 v0, 0xb000, v134
	v_pk_mul_f32 v[150:151], v[150:151], v[144:145]
	v_cvt_pk_bf16_f32 v144, v136, v137
	v_lshl_add_u64 v[136:137], v[0:1], 1, s[0:1]
	v_cvt_pk_bf16_f32 v145, v150, v151
	global_store_dwordx4 v[136:137], v[142:145], off sc0 sc1
; __device__ __forceinline__ unsigned pk2(float lo, float hi) { f32x2_t v = {lo, hi}; bf16x2_t b = __builtin_convertvector(v, bf16x2_t); return __builtin_bit_cast(unsigned, b); }
; __device__ __forceinline__ float fast_sigmoid(float z) { return __builtin_amdgcn_rcpf(1.0f + __expf(-z)); }
;     __device__ __forceinline__ void operator()(const f32x4 (&acc)[2][2][4][2], const pg8::Unit& u, int wr, int wc, int fr, int fq) const {
;     ...
; #pragma unroll
;             for (int ai = 0; ai < 2; ++ai)
; #pragma unroll
;                 for (int m = 0; m < 4; ++m) {
;                     const unsigned row = row0 + ai * 128 + m * 16; const float rs = rs8[ai * 4 + m];
;                     u32x4 w;
; #pragma unroll
;                     for (int n = 0; n < 2; ++n) {
;                         const f32x4 g = acc[ai][0][m][n] * rs, up = acc[ai][1][m][n] * rs; f32x4 hh;
; #pragma unroll
;                         for (int i = 0; i < 4; ++i) hh[i] = g[i] * fast_sigmoid(g[i]) * up[i];
;                         w[2 * n] = pk2(hh[0], hh[1]); w[2 * n + 1] = pk2(hh[2], hh[3]);
;                     }
;                     { bf16_t* hp_ = H + (row * (unsigned)FF + col0); asm volatile("global_store_dwordx4 %0, %1, off " H_STORE_BITS "\n\ts_nop 1" :: "v"(hp_), "v"(w) : "memory"); }
	s_nop 1
	v_pk_mul_f32 v[136:137], v[94:95], v[148:149] op_sel_hi:[1,0]
	s_nop 0
	v_mul_f32_e32 v0, 0xbfb8aa3b, v136
	v_exp_f32_e32 v0, v0
	s_nop 0
	v_add_f32_e32 v0, 1.0, v0
	v_rcp_f32_e32 v142, v0
	v_mul_f32_e32 v0, 0xbfb8aa3b, v137
	v_exp_f32_e32 v0, v0
	s_nop 0
	v_add_f32_e32 v0, 1.0, v0
	v_rcp_f32_e32 v143, v0
	s_nop 0
	v_pk_mul_f32 v[136:137], v[136:137], v[142:143]
	v_pk_mul_f32 v[142:143], v[86:87], v[148:149] op_sel_hi:[1,0]
	s_nop 0
	v_pk_mul_f32 v[136:137], v[142:143], v[136:137]
	v_pk_mul_f32 v[142:143], v[96:97], v[148:149] op_sel_hi:[1,0]
	s_nop 0
	v_mul_f32_e32 v0, 0xbfb8aa3b, v142
	v_exp_f32_e32 v0, v0
	s_nop 0
	v_add_f32_e32 v0, 1.0, v0
	v_rcp_f32_e32 v144, v0
	v_mul_f32_e32 v0, 0xbfb8aa3b, v143
	v_exp_f32_e32 v0, v0
	s_nop 0
	v_add_f32_e32 v0, 1.0, v0
	v_rcp_f32_e32 v145, v0
	s_nop 0
	v_pk_mul_f32 v[142:143], v[142:143], v[144:145]
	v_pk_mul_f32 v[144:145], v[88:89], v[148:149] op_sel_hi:[1,0]
	s_nop 0
	v_pk_mul_f32 v[144:145], v[144:145], v[142:143]
	v_cvt_pk_bf16_f32 v142, v136, v137
	v_pk_mul_f32 v[136:137], v[90:91], v[148:149] op_sel_hi:[1,0]
	v_cvt_pk_bf16_f32 v143, v144, v145
	v_mul_f32_e32 v0, 0xbfb8aa3b, v136
	v_exp_f32_e32 v0, v0
	s_nop 0
	v_add_f32_e32 v0, 1.0, v0
	v_rcp_f32_e32 v144, v0
	v_mul_f32_e32 v0, 0xbfb8aa3b, v137
	v_exp_f32_e32 v0, v0
	s_nop 0
	v_add_f32_e32 v0, 1.0, v0
	v_rcp_f32_e32 v145, v0
	s_nop 0
	v_pk_mul_f32 v[136:137], v[136:137], v[144:145]
	v_pk_mul_f32 v[144:145], v[82:83], v[148:149] op_sel_hi:[1,0]
	s_nop 0
	v_pk_mul_f32 v[136:137], v[144:145], v[136:137]
	v_pk_mul_f32 v[144:145], v[92:93], v[148:149] op_sel_hi:[1,0]
	v_pk_mul_f32 v[148:149], v[84:85], v[148:149] op_sel_hi:[1,0]
	v_mul_f32_e32 v0, 0xbfb8aa3b, v144
	v_exp_f32_e32 v0, v0
	s_nop 0
	v_add_f32_e32 v0, 1.0, v0
	v_rcp_f32_e32 v150, v0
	v_mul_f32_e32 v0, 0xbfb8aa3b, v145
	v_exp_f32_e32 v0, v0
	s_nop 0
	v_add_f32_e32 v0, 1.0, v0
	v_rcp_f32_e32 v151, v0
	v_add_u32_e32 v0, 0x16000, v134
	v_pk_mul_f32 v[144:145], v[144:145], v[150:151]
	s_nop 0
	v_pk_mul_f32 v[148:149], v[148:149], v[144:145]
	v_cvt_pk_bf16_f32 v144, v136, v137
	v_lshl_add_u64 v[136:137], v[0:1], 1, s[0:1]
	v_cvt_pk_bf16_f32 v145, v148, v149
	global_store_dwordx4 v[136:137], v[142:145], off sc0 sc1
	s_nop 1
	v_pk_mul_f32 v[136:137], v[78:79], v[146:147] op_sel_hi:[1,0]
	s_nop 0
	v_mul_f32_e32 v0, 0xbfb8aa3b, v136
	v_exp_f32_e32 v0, v0
	s_nop 0
	v_add_f32_e32 v0, 1.0, v0
	v_rcp_f32_e32 v142, v0
	v_mul_f32_e32 v0, 0xbfb8aa3b, v137
	v_exp_f32_e32 v0, v0
	s_nop 0
	v_add_f32_e32 v0, 1.0, v0
	v_rcp_f32_e32 v143, v0
	s_nop 0
	v_pk_mul_f32 v[136:137], v[136:137], v[142:143]
	v_pk_mul_f32 v[142:143], v[70:71], v[146:147] op_sel_hi:[1,0]
	s_nop 0
	v_pk_mul_f32 v[136:137], v[142:143], v[136:137]
	v_pk_mul_f32 v[142:143], v[80:81], v[146:147] op_sel_hi:[1,0]
	s_nop 0
	v_mul_f32_e32 v0, 0xbfb8aa3b, v142
	v_exp_f32_e32 v0, v0
	s_nop 0
	v_add_f32_e32 v0, 1.0, v0
	v_rcp_f32_e32 v144, v0
	v_mul_f32_e32 v0, 0xbfb8aa3b, v143
	v_exp_f32_e32 v0, v0
	s_nop 0
	v_add_f32_e32 v0, 1.0, v0
	v_rcp_f32_e32 v145, v0
	s_nop 0
	v_pk_mul_f32 v[142:143], v[142:143], v[144:145]
	v_pk_mul_f32 v[144:145], v[72:73], v[146:147] op_sel_hi:[1,0]
	s_nop 0
	v_pk_mul_f32 v[144:145], v[144:145], v[142:143]
	v_cvt_pk_bf16_f32 v142, v136, v137
	v_pk_mul_f32 v[136:137], v[74:75], v[146:147] op_sel_hi:[1,0]
	v_cvt_pk_bf16_f32 v143, v144, v145
	v_mul_f32_e32 v0, 0xbfb8aa3b, v136
	v_exp_f32_e32 v0, v0
	s_nop 0
	v_add_f32_e32 v0, 1.0, v0
	v_rcp_f32_e32 v144, v0
	v_mul_f32_e32 v0, 0xbfb8aa3b, v137
	v_exp_f32_e32 v0, v0
	s_nop 0
	v_add_f32_e32 v0, 1.0, v0
	v_rcp_f32_e32 v145, v0
	s_nop 0
	v_pk_mul_f32 v[136:137], v[136:137], v[144:145]
	v_pk_mul_f32 v[144:145], v[66:67], v[146:147] op_sel_hi:[1,0]
	s_nop 0
	v_pk_mul_f32 v[136:137], v[144:145], v[136:137]
	v_pk_mul_f32 v[144:145], v[76:77], v[146:147] op_sel_hi:[1,0]
	v_pk_mul_f32 v[146:147], v[68:69], v[146:147] op_sel_hi:[1,0]
	v_mul_f32_e32 v0, 0xbfb8aa3b, v144
	v_exp_f32_e32 v0, v0
	s_nop 0
	v_add_f32_e32 v0, 1.0, v0
	v_rcp_f32_e32 v148, v0
	v_mul_f32_e32 v0, 0xbfb8aa3b, v145
	v_exp_f32_e32 v0, v0
	s_nop 0
	v_add_f32_e32 v0, 1.0, v0
	v_rcp_f32_e32 v149, v0
	v_add_u32_e32 v0, 0x21000, v134
	v_pk_mul_f32 v[144:145], v[144:145], v[148:149]
	s_nop 0
	v_pk_mul_f32 v[146:147], v[146:147], v[144:145]
	v_cvt_pk_bf16_f32 v144, v136, v137
	v_lshl_add_u64 v[136:137], v[0:1], 1, s[0:1]
	v_cvt_pk_bf16_f32 v145, v146, v147
	global_store_dwordx4 v[136:137], v[142:145], off
	s_nop 1
	v_pk_mul_f32 v[136:137], v[62:63], v[140:141] op_sel_hi:[1,0]
	s_nop 0
	v_mul_f32_e32 v0, 0xbfb8aa3b, v136
	v_exp_f32_e32 v0, v0
	s_nop 0
	v_add_f32_e32 v0, 1.0, v0
	v_rcp_f32_e32 v142, v0
	v_mul_f32_e32 v0, 0xbfb8aa3b, v137
	v_exp_f32_e32 v0, v0
	s_nop 0
	v_add_f32_e32 v0, 1.0, v0
	v_rcp_f32_e32 v143, v0
	s_nop 0
	v_pk_mul_f32 v[136:137], v[136:137], v[142:143]
	v_pk_mul_f32 v[142:143], v[54:55], v[140:141] op_sel_hi:[1,0]
	s_nop 0
	v_pk_mul_f32 v[136:137], v[142:143], v[136:137]
	v_pk_mul_f32 v[142:143], v[64:65], v[140:141] op_sel_hi:[1,0]
	s_nop 0
	v_mul_f32_e32 v0, 0xbfb8aa3b, v142
	v_exp_f32_e32 v0, v0
	s_nop 0
	v_add_f32_e32 v0, 1.0, v0
	v_rcp_f32_e32 v144, v0
	v_mul_f32_e32 v0, 0xbfb8aa3b, v143
	v_exp_f32_e32 v0, v0
	s_nop 0
	v_add_f32_e32 v0, 1.0, v0
	v_rcp_f32_e32 v145, v0
	s_nop 0
	v_pk_mul_f32 v[142:143], v[142:143], v[144:145]
	v_pk_mul_f32 v[144:145], v[56:57], v[140:141] op_sel_hi:[1,0]
	s_nop 0
	v_pk_mul_f32 v[144:145], v[144:145], v[142:143]
	v_cvt_pk_bf16_f32 v142, v136, v137
	v_pk_mul_f32 v[136:137], v[58:59], v[140:141] op_sel_hi:[1,0]
	v_cvt_pk_bf16_f32 v143, v144, v145
	v_mul_f32_e32 v0, 0xbfb8aa3b, v136
	v_exp_f32_e32 v0, v0
	s_nop 0
	v_add_f32_e32 v0, 1.0, v0
	v_rcp_f32_e32 v144, v0
; __device__ __forceinline__ unsigned pk2(float lo, float hi) { f32x2_t v = {lo, hi}; bf16x2_t b = __builtin_convertvector(v, bf16x2_t); return __builtin_bit_cast(unsigned, b); }
; __device__ __forceinline__ float fast_sigmoid(float z) { return __builtin_amdgcn_rcpf(1.0f + __expf(-z)); }
;     __device__ __forceinline__ void operator()(const f32x4 (&acc)[2][2][4][2], const pg8::Unit& u, int wr, int wc, int fr, int fq) const {
;     ...
; #pragma unroll
;             for (int ai = 0; ai < 2; ++ai)
; #pragma unroll
;                 for (int m = 0; m < 4; ++m) {
;                     const unsigned row = row0 + ai * 128 + m * 16; const float rs = rs8[ai * 4 + m];
;                     u32x4 w;
; #pragma unroll
;                     for (int n = 0; n < 2; ++n) {
;                         const f32x4 g = acc[ai][0][m][n] * rs, up = acc[ai][1][m][n] * rs; f32x4 hh;
; #pragma unroll
;                         for (int i = 0; i < 4; ++i) hh[i] = g[i] * fast_sigmoid(g[i]) * up[i];
;                         w[2 * n] = pk2(hh[0], hh[1]); w[2 * n + 1] = pk2(hh[2], hh[3]);
;                     }
;                     { bf16_t* hp_ = H + (row * (unsigned)FF + col0); asm volatile("global_store_dwordx4 %0, %1, off " H_STORE_BITS "\n\ts_nop 1" :: "v"(hp_), "v"(w) : "memory"); }
	v_mul_f32_e32 v0, 0xbfb8aa3b, v137
	v_exp_f32_e32 v0, v0
	s_nop 0
	v_add_f32_e32 v0, 1.0, v0
	v_rcp_f32_e32 v145, v0
	s_nop 0
	v_pk_mul_f32 v[136:137], v[136:137], v[144:145]
	v_pk_mul_f32 v[144:145], v[50:51], v[140:141] op_sel_hi:[1,0]
	s_nop 0
	v_pk_mul_f32 v[136:137], v[144:145], v[136:137]
	v_pk_mul_f32 v[144:145], v[60:61], v[140:141] op_sel_hi:[1,0]
	v_pk_mul_f32 v[140:141], v[52:53], v[140:141] op_sel_hi:[1,0]
	v_mul_f32_e32 v0, 0xbfb8aa3b, v144
	v_exp_f32_e32 v0, v0
	s_nop 0
	v_add_f32_e32 v0, 1.0, v0
	v_rcp_f32_e32 v146, v0
	v_mul_f32_e32 v0, 0xbfb8aa3b, v145
	v_exp_f32_e32 v0, v0
	s_nop 0
	v_add_f32_e32 v0, 1.0, v0
	v_rcp_f32_e32 v147, v0
	v_add_u32_e32 v0, 0x58000, v134
	v_pk_mul_f32 v[144:145], v[144:145], v[146:147]
	s_nop 0
	v_pk_mul_f32 v[140:141], v[140:141], v[144:145]
	v_cvt_pk_bf16_f32 v144, v136, v137
	v_lshl_add_u64 v[136:137], v[0:1], 1, s[0:1]
	v_cvt_pk_bf16_f32 v145, v140, v141
	global_store_dwordx4 v[136:137], v[142:145], off
	s_nop 1
	v_pk_mul_f32 v[136:137], v[46:47], v[138:139] op_sel_hi:[1,0]
	s_nop 0
	v_mul_f32_e32 v0, 0xbfb8aa3b, v136
	v_exp_f32_e32 v0, v0
	s_nop 0
	v_add_f32_e32 v0, 1.0, v0
	v_rcp_f32_e32 v140, v0
	v_mul_f32_e32 v0, 0xbfb8aa3b, v137
	v_exp_f32_e32 v0, v0
	s_nop 0
	v_add_f32_e32 v0, 1.0, v0
	v_rcp_f32_e32 v141, v0
	s_nop 0
	v_pk_mul_f32 v[136:137], v[136:137], v[140:141]
	v_pk_mul_f32 v[140:141], v[38:39], v[138:139] op_sel_hi:[1,0]
	s_nop 0
	v_pk_mul_f32 v[136:137], v[140:141], v[136:137]
	v_pk_mul_f32 v[140:141], v[48:49], v[138:139] op_sel_hi:[1,0]
	v_cvt_pk_bf16_f32 v136, v136, v137
	v_mul_f32_e32 v0, 0xbfb8aa3b, v140
	v_exp_f32_e32 v0, v0
	s_nop 0
	v_add_f32_e32 v0, 1.0, v0
	v_rcp_f32_e32 v142, v0
	v_mul_f32_e32 v0, 0xbfb8aa3b, v141
	v_exp_f32_e32 v0, v0
	s_nop 0
	v_add_f32_e32 v0, 1.0, v0
	v_rcp_f32_e32 v143, v0
	s_nop 0
	v_pk_mul_f32 v[140:141], v[140:141], v[142:143]
	v_pk_mul_f32 v[142:143], v[40:41], v[138:139] op_sel_hi:[1,0]
	s_nop 0
	v_pk_mul_f32 v[140:141], v[142:143], v[140:141]
	s_nop 0
	v_cvt_pk_bf16_f32 v137, v140, v141
	v_pk_mul_f32 v[140:141], v[42:43], v[138:139] op_sel_hi:[1,0]
	s_nop 0
	v_mul_f32_e32 v0, 0xbfb8aa3b, v140
	v_exp_f32_e32 v0, v0
	s_nop 0
	v_add_f32_e32 v0, 1.0, v0
	v_rcp_f32_e32 v142, v0
	v_mul_f32_e32 v0, 0xbfb8aa3b, v141
	v_exp_f32_e32 v0, v0
	s_nop 0
	v_add_f32_e32 v0, 1.0, v0
	v_rcp_f32_e32 v143, v0
	s_nop 0
	v_pk_mul_f32 v[140:141], v[140:141], v[142:143]
	v_pk_mul_f32 v[142:143], v[34:35], v[138:139] op_sel_hi:[1,0]
	s_nop 0
	v_pk_mul_f32 v[140:141], v[142:143], v[140:141]
	v_pk_mul_f32 v[142:143], v[44:45], v[138:139] op_sel_hi:[1,0]
	v_pk_mul_f32 v[138:139], v[36:37], v[138:139] op_sel_hi:[1,0]
	v_mul_f32_e32 v0, 0xbfb8aa3b, v142
	v_exp_f32_e32 v0, v0
	s_nop 0
	v_add_f32_e32 v0, 1.0, v0
	v_rcp_f32_e32 v144, v0
	v_mul_f32_e32 v0, 0xbfb8aa3b, v143
	v_exp_f32_e32 v0, v0
	s_nop 0
	v_add_f32_e32 v0, 1.0, v0
	v_rcp_f32_e32 v145, v0
	v_add_u32_e32 v0, 0x63000, v134
	v_pk_mul_f32 v[142:143], v[142:143], v[144:145]
	s_nop 0
	v_pk_mul_f32 v[142:143], v[138:139], v[142:143]
	v_cvt_pk_bf16_f32 v138, v140, v141
	v_cvt_pk_bf16_f32 v139, v142, v143
	v_lshl_add_u64 v[140:141], v[0:1], 1, s[0:1]
	global_store_dwordx4 v[140:141], v[136:139], off
	s_nop 1
	v_pk_mul_f32 v[136:137], v[30:31], v[132:133] op_sel_hi:[1,0]
	s_nop 0
	v_mul_f32_e32 v0, 0xbfb8aa3b, v136
	v_exp_f32_e32 v0, v0
	s_nop 0
	v_add_f32_e32 v0, 1.0, v0
	v_rcp_f32_e32 v138, v0
	v_mul_f32_e32 v0, 0xbfb8aa3b, v137
	v_exp_f32_e32 v0, v0
	s_nop 0
	v_add_f32_e32 v0, 1.0, v0
	v_rcp_f32_e32 v139, v0
	s_nop 0
	v_pk_mul_f32 v[136:137], v[136:137], v[138:139]
	v_pk_mul_f32 v[138:139], v[22:23], v[132:133] op_sel_hi:[1,0]
	s_nop 0
	v_pk_mul_f32 v[136:137], v[138:139], v[136:137]
	v_pk_mul_f32 v[138:139], v[32:33], v[132:133] op_sel_hi:[1,0]
	v_cvt_pk_bf16_f32 v136, v136, v137
	v_mul_f32_e32 v0, 0xbfb8aa3b, v138
; __device__ __forceinline__ unsigned pk2(float lo, float hi) { f32x2_t v = {lo, hi}; bf16x2_t b = __builtin_convertvector(v, bf16x2_t); return __builtin_bit_cast(unsigned, b); }
; __device__ __forceinline__ float fast_sigmoid(float z) { return __builtin_amdgcn_rcpf(1.0f + __expf(-z)); }
;     __device__ __forceinline__ void operator()(const f32x4 (&acc)[2][2][4][2], const pg8::Unit& u, int wr, int wc, int fr, int fq) const {
;     ...
; #pragma unroll
;             for (int ai = 0; ai < 2; ++ai)
; #pragma unroll
;                 for (int m = 0; m < 4; ++m) {
;                     const unsigned row = row0 + ai * 128 + m * 16; const float rs = rs8[ai * 4 + m];
;                     u32x4 w;
; #pragma unroll
;                     for (int n = 0; n < 2; ++n) {
;                         const f32x4 g = acc[ai][0][m][n] * rs, up = acc[ai][1][m][n] * rs; f32x4 hh;
; #pragma unroll
;                         for (int i = 0; i < 4; ++i) hh[i] = g[i] * fast_sigmoid(g[i]) * up[i];
;                         w[2 * n] = pk2(hh[0], hh[1]); w[2 * n + 1] = pk2(hh[2], hh[3]);
;                     }
;                     { bf16_t* hp_ = H + (row * (unsigned)FF + col0); asm volatile("global_store_dwordx4 %0, %1, off " H_STORE_BITS "\n\ts_nop 1" :: "v"(hp_), "v"(w) : "memory"); }
	v_exp_f32_e32 v0, v0
	s_nop 0
	v_add_f32_e32 v0, 1.0, v0
	v_rcp_f32_e32 v140, v0
	v_mul_f32_e32 v0, 0xbfb8aa3b, v139
	v_exp_f32_e32 v0, v0
	s_nop 0
	v_add_f32_e32 v0, 1.0, v0
	v_rcp_f32_e32 v141, v0
	s_nop 0
	v_pk_mul_f32 v[138:139], v[138:139], v[140:141]
	v_pk_mul_f32 v[140:141], v[24:25], v[132:133] op_sel_hi:[1,0]
	s_nop 0
	v_pk_mul_f32 v[138:139], v[140:141], v[138:139]
	s_nop 0
	v_cvt_pk_bf16_f32 v137, v138, v139
	v_pk_mul_f32 v[138:139], v[26:27], v[132:133] op_sel_hi:[1,0]
	s_nop 0
	v_mul_f32_e32 v0, 0xbfb8aa3b, v138
	v_exp_f32_e32 v0, v0
	s_nop 0
	v_add_f32_e32 v0, 1.0, v0
	v_rcp_f32_e32 v140, v0
	v_mul_f32_e32 v0, 0xbfb8aa3b, v139
	v_exp_f32_e32 v0, v0
	s_nop 0
	v_add_f32_e32 v0, 1.0, v0
	v_rcp_f32_e32 v141, v0
	s_nop 0
	v_pk_mul_f32 v[138:139], v[138:139], v[140:141]
	v_pk_mul_f32 v[140:141], v[18:19], v[132:133] op_sel_hi:[1,0]
	s_nop 0
	v_pk_mul_f32 v[138:139], v[140:141], v[138:139]
	v_pk_mul_f32 v[140:141], v[28:29], v[132:133] op_sel_hi:[1,0]
	v_pk_mul_f32 v[132:133], v[20:21], v[132:133] op_sel_hi:[1,0]
	v_mul_f32_e32 v0, 0xbfb8aa3b, v140
	v_exp_f32_e32 v0, v0
	v_cvt_pk_bf16_f32 v138, v138, v139
	v_add_f32_e32 v0, 1.0, v0
	v_rcp_f32_e32 v142, v0
	v_mul_f32_e32 v0, 0xbfb8aa3b, v141
	v_exp_f32_e32 v0, v0
	s_nop 0
	v_add_f32_e32 v0, 1.0, v0
	v_rcp_f32_e32 v143, v0
	v_add_u32_e32 v0, 0x6e000, v134
	v_pk_mul_f32 v[140:141], v[140:141], v[142:143]
	s_nop 0
	v_pk_mul_f32 v[132:133], v[132:133], v[140:141]
	s_nop 0
	v_cvt_pk_bf16_f32 v139, v132, v133
	v_lshl_add_u64 v[132:133], v[0:1], 1, s[0:1]
	global_store_dwordx4 v[132:133], v[136:139], off
	s_nop 1
	v_pk_mul_f32 v[132:133], v[14:15], v[130:131] op_sel_hi:[1,0]
	s_nop 0
	v_mul_f32_e32 v0, 0xbfb8aa3b, v132
	v_exp_f32_e32 v0, v0
	s_nop 0
	v_add_f32_e32 v0, 1.0, v0
	v_rcp_f32_e32 v136, v0
	v_mul_f32_e32 v0, 0xbfb8aa3b, v133
	v_exp_f32_e32 v0, v0
	s_nop 0
	v_add_f32_e32 v0, 1.0, v0
	v_rcp_f32_e32 v137, v0
	s_nop 0
	v_pk_mul_f32 v[132:133], v[132:133], v[136:137]
	v_pk_mul_f32 v[136:137], v[6:7], v[130:131] op_sel_hi:[1,0]
	s_nop 0
	v_pk_mul_f32 v[132:133], v[136:137], v[132:133]
	v_pk_mul_f32 v[136:137], v[16:17], v[130:131] op_sel_hi:[1,0]
	s_nop 0
	v_mul_f32_e32 v0, 0xbfb8aa3b, v136
	v_exp_f32_e32 v0, v0
	s_nop 0
	v_add_f32_e32 v0, 1.0, v0
	v_rcp_f32_e32 v138, v0
	v_mul_f32_e32 v0, 0xbfb8aa3b, v137
	v_exp_f32_e32 v0, v0
	s_nop 0
	v_add_f32_e32 v0, 1.0, v0
	v_rcp_f32_e32 v139, v0
	s_nop 0
	v_pk_mul_f32 v[136:137], v[136:137], v[138:139]
	v_pk_mul_f32 v[138:139], v[8:9], v[130:131] op_sel_hi:[1,0]
	s_nop 0
	v_pk_mul_f32 v[138:139], v[138:139], v[136:137]
	v_cvt_pk_bf16_f32 v136, v132, v133
	v_pk_mul_f32 v[132:133], v[10:11], v[130:131] op_sel_hi:[1,0]
	v_cvt_pk_bf16_f32 v137, v138, v139
	v_mul_f32_e32 v0, 0xbfb8aa3b, v132
	v_exp_f32_e32 v0, v0
	s_nop 0
	v_add_f32_e32 v0, 1.0, v0
	v_rcp_f32_e32 v138, v0
	v_mul_f32_e32 v0, 0xbfb8aa3b, v133
	v_exp_f32_e32 v0, v0
	s_nop 0
	v_add_f32_e32 v0, 1.0, v0
	v_rcp_f32_e32 v139, v0
	s_nop 0
	v_pk_mul_f32 v[132:133], v[132:133], v[138:139]
	v_pk_mul_f32 v[138:139], v[2:3], v[130:131] op_sel_hi:[1,0]
	s_nop 0
	v_pk_mul_f32 v[132:133], v[138:139], v[132:133]
	v_pk_mul_f32 v[138:139], v[12:13], v[130:131] op_sel_hi:[1,0]
	v_pk_mul_f32 v[130:131], v[4:5], v[130:131] op_sel_hi:[1,0]
	v_mul_f32_e32 v0, 0xbfb8aa3b, v138
	v_exp_f32_e32 v0, v0
	s_nop 0
	v_add_f32_e32 v0, 1.0, v0
	v_rcp_f32_e32 v140, v0
	v_mul_f32_e32 v0, 0xbfb8aa3b, v139
	v_exp_f32_e32 v0, v0
	s_nop 0
	v_add_f32_e32 v0, 1.0, v0
	v_rcp_f32_e32 v141, v0
	v_add_u32_e32 v0, 0x79000, v134
	v_pk_mul_f32 v[138:139], v[138:139], v[140:141]
	s_nop 0
	v_pk_mul_f32 v[130:131], v[130:131], v[138:139]
	v_cvt_pk_bf16_f32 v138, v132, v133
	v_cvt_pk_bf16_f32 v139, v130, v131
	v_lshl_add_u64 v[130:131], v[0:1], 1, s[0:1]
	global_store_dwordx4 v[130:131], v[136:139], off
	s_nop 1
	s_mov_b64 s[0:1], 0
